# ssd_s3 B and X causal-conv loops: the four taps of a row are loaded together one row ahead (were four exec-masked load-and-wait blocks per row)
# speedup vs baseline: 1.0220x; 1.0079x over previous
.LBB0_2269:
	s_or_b64 exec, exec, s[30:31]
	v_cndmask_b32_e64 v2, 0, 1, s[34:35]
	s_lshr_b32 s4, s2, 1
	v_lshlrev_b32_e32 v58, 8, v2
	v_or_b32_e32 v2, s96, v129
	s_and_b32 s4, s4, 63
	v_lshlrev_b32_e32 v10, 2, v2
	s_lshl_b32 s30, s4, 8
	v_lshl_add_u64 v[46:47], s[28:29], 0, v[10:11]
	v_lshl_add_u64 v[44:45], s[26:27], 0, v[10:11]
	s_waitcnt lgkmcnt(0)
	s_barrier
	s_and_saveexec_b64 s[16:17], s[8:9]
	s_cbranch_execz .LBB0_2280
	s_mov_b64 s[4:5], 0x400
	v_lshl_add_u64 v[24:25], v[44:45], 0, s[4:5]
	s_mov_b64 s[4:5], 0x1c00
	v_lshl_add_u64 v[36:37], v[44:45], 0, s[4:5]
	s_mov_b64 s[4:5], 0x2800
	v_lshl_add_u64 v[40:41], v[44:45], 0, s[4:5]
	s_movk_i32 s4, 0x1000
	v_add_co_u32_e32 v28, vcc, s4, v44
	s_movk_i32 s4, 0x2000
	s_nop 0
	v_addc_co_u32_e32 v29, vcc, 0, v45, vcc
	global_load_dwordx4 v[2:5], v[46:47], off offset:1040
	global_load_dwordx4 v[6:9], v[46:47], off offset:1024
	global_load_dwordx4 v[12:15], v[44:45], off offset:1040
	global_load_dwordx4 v[16:19], v[44:45], off offset:1024
	global_load_dwordx4 v[20:23], v[24:25], off offset:3088
	s_nop 0
	global_load_dwordx4 v[24:27], v[24:25], off offset:3072
	v_add_co_u32_e32 v32, vcc, s4, v44
	s_add_u32 s4, s30, s24
	s_nop 0
	v_addc_co_u32_e32 v33, vcc, 0, v45, vcc
	global_load_dwordx4 v[28:31], v[28:29], off offset:3072
	s_nop 0
	global_load_dwordx4 v[32:35], v[32:33], off offset:2048
	s_nop 0
	global_load_dwordx4 v[36:39], v[36:37], off offset:16
	s_nop 0
	global_load_dwordx4 v[40:43], v[40:41], off offset:16
	s_addc_u32 s5, 0, s25
	v_lshl_add_u64 v[50:51], s[4:5], 0, v[68:69]
	v_mad_u64_u32 v[52:53], s[4:5], v50, s64, 0
	v_lshl_add_u64 v[48:49], s[90:91], 0, v[72:73]
	v_mad_i32_i24 v51, v51, s64, v53
	v_or_b32_e32 v50, v52, v58
	v_lshl_add_u64 v[48:49], v[48:49], 0, v[50:51]
	s_mov_b64 s[4:5], 0x97fca00
	v_lshl_add_u64 v[48:49], v[48:49], 0, s[4:5]
	s_mov_b64 s[26:27], 0
	v_mov_b32_e32 v10, v136
	v_mov_b32_e32 v59, v68
	s_add_u32 s50, s60, 0x1000
	s_addc_u32 s51, s61, 0
	s_add_u32 s98, s60, 0x4000
	s_addc_u32 s99, s61, 0
	v_add_co_u32_e32 v198, vcc, 0x1000, v48
	v_addc_co_u32_e32 v199, vcc, 0, v49, vcc
	v_add_co_u32_e32 v200, vcc, 0x4000, v48
	v_addc_co_u32_e32 v201, vcc, 0, v49, vcc
	global_load_dwordx4 v[150:153], v[198:199], off offset:-4096
	global_load_dwordx4 v[154:157], v[198:199], off offset:2048
	global_load_dwordx4 v[158:161], v[200:201], off offset:-4096
	global_load_dwordx4 v[162:165], v[200:201], off offset:2048
	s_branch .LBB0_2272

.LBB0_2272:
	s_waitcnt vmcnt(0)
	v_mov_b64_e32 v[182:183], v[150:151]
	v_mov_b64_e32 v[184:185], v[152:153]
	v_mov_b64_e32 v[186:187], v[154:155]
	v_mov_b64_e32 v[188:189], v[156:157]
	v_mov_b64_e32 v[190:191], v[158:159]
	v_mov_b64_e32 v[192:193], v[160:161]
	v_mov_b64_e32 v[194:195], v[162:163]
	v_mov_b64_e32 v[196:197], v[164:165]
	v_lshl_add_u64 v[198:199], v[48:49], 0, s[50:51]
	v_lshl_add_u64 v[200:201], v[48:49], 0, s[98:99]
	global_load_dwordx4 v[150:153], v[198:199], off offset:-4096
	global_load_dwordx4 v[154:157], v[198:199], off offset:2048
	global_load_dwordx4 v[158:161], v[200:201], off offset:-4096
	global_load_dwordx4 v[162:165], v[200:201], off offset:2048
	v_add_u32_e32 v60, s30, v59
	v_cmp_lt_i32_e32 vcc, 2, v60
	v_mov_b64_e32 v[50:51], v[4:5]
	v_mov_b64_e32 v[52:53], v[2:3]
	v_mov_b64_e32 v[54:55], v[8:9]
	v_mov_b64_e32 v[56:57], v[6:7]
	s_and_saveexec_b64 s[28:29], vcc
	s_cbranch_execnz .LBB0_2276
	s_or_b64 exec, exec, s[28:29]
	v_cmp_lt_i32_e32 vcc, 1, v60
	s_and_saveexec_b64 s[28:29], vcc
	s_cbranch_execnz .LBB0_2277

.LBB0_2276:
	v_and_b32_e32 v55, 0xffff0000, v182
	v_lshlrev_b32_e32 v54, 16, v182
	v_and_b32_e32 v63, 0xffff0000, v183
	v_lshlrev_b32_e32 v62, 16, v183
	v_and_b32_e32 v51, 0xffff0000, v184
	v_lshlrev_b32_e32 v50, 16, v184
	v_and_b32_e32 v85, 0xffff0000, v185
	v_lshlrev_b32_e32 v84, 16, v185
	v_pk_fma_f32 v[56:57], v[16:17], v[54:55], v[6:7]
	v_pk_fma_f32 v[54:55], v[18:19], v[62:63], v[8:9]
	v_pk_fma_f32 v[52:53], v[12:13], v[50:51], v[2:3]
	v_pk_fma_f32 v[50:51], v[14:15], v[84:85], v[4:5]
	s_or_b64 exec, exec, s[28:29]
	v_cmp_lt_i32_e32 vcc, 1, v60
	s_and_saveexec_b64 s[28:29], vcc
	s_cbranch_execz .LBB0_2274
.LBB0_2277:
	v_and_b32_e32 v63, 0xffff0000, v186
	v_lshlrev_b32_e32 v62, 16, v186
	v_pk_fma_f32 v[56:57], v[24:25], v[62:63], v[56:57]
	v_and_b32_e32 v63, 0xffff0000, v187
	v_lshlrev_b32_e32 v62, 16, v187
	v_pk_fma_f32 v[54:55], v[26:27], v[62:63], v[54:55]
	v_and_b32_e32 v63, 0xffff0000, v188
	v_lshlrev_b32_e32 v62, 16, v188
	v_pk_fma_f32 v[52:53], v[20:21], v[62:63], v[52:53]
	v_and_b32_e32 v63, 0xffff0000, v189
	v_lshlrev_b32_e32 v62, 16, v189
	v_pk_fma_f32 v[50:51], v[22:23], v[62:63], v[50:51]
	s_or_b64 exec, exec, s[28:29]
	v_cmp_lt_i32_e32 vcc, 0, v60
	s_and_saveexec_b64 s[28:29], vcc
	s_cbranch_execz .LBB0_2275
.LBB0_2278:
	v_and_b32_e32 v63, 0xffff0000, v190
	v_lshlrev_b32_e32 v62, 16, v190
	v_pk_fma_f32 v[56:57], v[28:29], v[62:63], v[56:57]
	v_and_b32_e32 v63, 0xffff0000, v191
	v_lshlrev_b32_e32 v62, 16, v191
	v_pk_fma_f32 v[54:55], v[30:31], v[62:63], v[54:55]
	v_and_b32_e32 v63, 0xffff0000, v192
	v_lshlrev_b32_e32 v62, 16, v192
	v_pk_fma_f32 v[52:53], v[36:37], v[62:63], v[52:53]
	v_and_b32_e32 v63, 0xffff0000, v193
	v_lshlrev_b32_e32 v62, 16, v193
	v_pk_fma_f32 v[50:51], v[38:39], v[62:63], v[50:51]
	s_or_b64 exec, exec, s[28:29]
	v_cmp_lt_i32_e32 vcc, -1, v60
	s_and_saveexec_b64 s[28:29], vcc
	s_cbranch_execz .LBB0_2271
.LBB0_2279:
	v_and_b32_e32 v85, 0xffff0000, v194
	v_lshlrev_b32_e32 v84, 16, v194
	v_pk_fma_f32 v[56:57], v[32:33], v[84:85], v[56:57]
	v_and_b32_e32 v85, 0xffff0000, v195
	v_lshlrev_b32_e32 v84, 16, v195
	v_and_b32_e32 v61, 0xffff0000, v196
	v_lshlrev_b32_e32 v60, 16, v196
	v_pk_fma_f32 v[52:53], v[40:41], v[60:61], v[52:53]
	v_and_b32_e32 v61, 0xffff0000, v197
	v_lshlrev_b32_e32 v60, 16, v197
	v_pk_fma_f32 v[54:55], v[34:35], v[84:85], v[54:55]
	v_pk_fma_f32 v[50:51], v[42:43], v[60:61], v[50:51]
	s_branch .LBB0_2271
.LBB0_2280:
	s_waitcnt vmcnt(0)
	s_or_b64 exec, exec, s[16:17]
	s_and_saveexec_b64 s[16:17], s[8:9]
	s_cbranch_execz .LBB0_2291
	s_mov_b64 s[4:5], 0x1800
	s_waitcnt vmcnt(1)
	v_lshl_add_u64 v[36:37], v[44:45], 0, s[4:5]
	s_mov_b64 s[4:5], 0x2400
	s_waitcnt vmcnt(0)
	v_lshl_add_u64 v[40:41], v[44:45], 0, s[4:5]
	s_movk_i32 s4, 0x1000
	v_add_co_u32_e32 v28, vcc, s4, v44
	s_movk_i32 s4, 0x2000
	s_nop 0
	v_addc_co_u32_e32 v29, vcc, 0, v45, vcc
	global_load_dwordx4 v[2:5], v[46:47], off offset:16
	global_load_dwordx4 v[6:9], v[46:47], off
	global_load_dwordx4 v[12:15], v[44:45], off offset:16
	global_load_dwordx4 v[16:19], v[44:45], off
	global_load_dwordx4 v[20:23], v[44:45], off offset:3088
	global_load_dwordx4 v[24:27], v[44:45], off offset:3072
	v_add_co_u32_e32 v32, vcc, s4, v44
	s_add_u32 s4, s30, s24
	s_nop 0
	v_addc_co_u32_e32 v33, vcc, 0, v45, vcc
	global_load_dwordx4 v[28:31], v[28:29], off offset:2048
	s_nop 0
	global_load_dwordx4 v[32:35], v[32:33], off offset:1024
	s_nop 0
	global_load_dwordx4 v[36:39], v[36:37], off offset:16
	s_nop 0
	global_load_dwordx4 v[40:43], v[40:41], off offset:16
	s_addc_u32 s5, 0, s25
	v_lshl_add_u64 v[46:47], s[4:5], 0, v[68:69]
	v_mad_u64_u32 v[48:49], s[4:5], v46, s64, 0
	v_lshl_add_u64 v[44:45], s[90:91], 0, v[72:73]
	v_mad_i32_i24 v47, v47, s64, v49
	v_or_b32_e32 v46, v48, v58
	v_lshl_add_u64 v[44:45], v[44:45], 0, v[46:47]
	s_mov_b64 s[4:5], 0x97fc800
	v_lshl_add_u64 v[44:45], v[44:45], 0, s[4:5]
	s_mov_b64 s[24:25], 0
	v_mov_b32_e32 v10, v138
	v_mov_b32_e32 v54, v137
	v_mov_b32_e32 v55, v68
	s_add_u32 s50, s60, 0x1000
	s_addc_u32 s51, s61, 0
	s_add_u32 s98, s60, 0x4000
	s_addc_u32 s99, s61, 0
	v_add_co_u32_e32 v198, vcc, 0x1000, v44
	v_addc_co_u32_e32 v199, vcc, 0, v45, vcc
	v_add_co_u32_e32 v200, vcc, 0x4000, v44
	v_addc_co_u32_e32 v201, vcc, 0, v45, vcc
	global_load_dwordx4 v[150:153], v[198:199], off offset:-4096
	global_load_dwordx4 v[154:157], v[198:199], off offset:2048
	global_load_dwordx4 v[158:161], v[200:201], off offset:-4096
	global_load_dwordx4 v[162:165], v[200:201], off offset:2048
	s_branch .LBB0_2283

.LBB0_2283:
	s_waitcnt vmcnt(0)
	v_mov_b64_e32 v[182:183], v[150:151]
	v_mov_b64_e32 v[184:185], v[152:153]
	v_mov_b64_e32 v[186:187], v[154:155]
	v_mov_b64_e32 v[188:189], v[156:157]
	v_mov_b64_e32 v[190:191], v[158:159]
	v_mov_b64_e32 v[192:193], v[160:161]
	v_mov_b64_e32 v[194:195], v[162:163]
	v_mov_b64_e32 v[196:197], v[164:165]
	v_lshl_add_u64 v[198:199], v[44:45], 0, s[50:51]
	v_lshl_add_u64 v[200:201], v[44:45], 0, s[98:99]
	global_load_dwordx4 v[150:153], v[198:199], off offset:-4096
	global_load_dwordx4 v[154:157], v[198:199], off offset:2048
	global_load_dwordx4 v[158:161], v[200:201], off offset:-4096
	global_load_dwordx4 v[162:165], v[200:201], off offset:2048
	v_add_u32_e32 v56, s30, v55
	v_cmp_lt_i32_e32 vcc, 2, v56
	v_mov_b64_e32 v[46:47], v[4:5]
	v_mov_b64_e32 v[48:49], v[2:3]
	v_mov_b64_e32 v[50:51], v[8:9]
	v_mov_b64_e32 v[52:53], v[6:7]
	s_and_saveexec_b64 s[26:27], vcc
	s_cbranch_execnz .LBB0_2287
	s_or_b64 exec, exec, s[26:27]
	v_cmp_lt_i32_e32 vcc, 1, v56
	s_and_saveexec_b64 s[26:27], vcc
	s_cbranch_execnz .LBB0_2288

.LBB0_2287:
	v_and_b32_e32 v51, 0xffff0000, v182
	v_lshlrev_b32_e32 v50, 16, v182
	v_and_b32_e32 v59, 0xffff0000, v183
	v_lshlrev_b32_e32 v58, 16, v183
	v_and_b32_e32 v47, 0xffff0000, v184
	v_lshlrev_b32_e32 v46, 16, v184
	v_and_b32_e32 v61, 0xffff0000, v185
	v_lshlrev_b32_e32 v60, 16, v185
	v_pk_fma_f32 v[52:53], v[16:17], v[50:51], v[6:7]
	v_pk_fma_f32 v[50:51], v[18:19], v[58:59], v[8:9]
	v_pk_fma_f32 v[48:49], v[12:13], v[46:47], v[2:3]
	v_pk_fma_f32 v[46:47], v[14:15], v[60:61], v[4:5]
	s_or_b64 exec, exec, s[26:27]
	v_cmp_lt_i32_e32 vcc, 1, v56
	s_and_saveexec_b64 s[26:27], vcc
	s_cbranch_execz .LBB0_2285
.LBB0_2288:
	v_and_b32_e32 v63, 0xffff0000, v186
	v_lshlrev_b32_e32 v62, 16, v186
	v_pk_fma_f32 v[52:53], v[24:25], v[62:63], v[52:53]
	v_and_b32_e32 v63, 0xffff0000, v187
	v_lshlrev_b32_e32 v62, 16, v187
	v_and_b32_e32 v59, 0xffff0000, v188
	v_lshlrev_b32_e32 v58, 16, v188
	v_pk_fma_f32 v[48:49], v[20:21], v[58:59], v[48:49]
	v_and_b32_e32 v59, 0xffff0000, v189
	v_lshlrev_b32_e32 v58, 16, v189
	v_pk_fma_f32 v[50:51], v[26:27], v[62:63], v[50:51]
	v_pk_fma_f32 v[46:47], v[22:23], v[58:59], v[46:47]
	s_or_b64 exec, exec, s[26:27]
	v_cmp_lt_i32_e32 vcc, 0, v56
	s_and_saveexec_b64 s[26:27], vcc
	s_cbranch_execz .LBB0_2286
.LBB0_2289:
	v_and_b32_e32 v63, 0xffff0000, v190
	v_lshlrev_b32_e32 v62, 16, v190
	v_pk_fma_f32 v[52:53], v[28:29], v[62:63], v[52:53]
	v_and_b32_e32 v63, 0xffff0000, v191
	v_lshlrev_b32_e32 v62, 16, v191
	v_and_b32_e32 v59, 0xffff0000, v192
	v_lshlrev_b32_e32 v58, 16, v192
	v_pk_fma_f32 v[48:49], v[36:37], v[58:59], v[48:49]
	v_and_b32_e32 v59, 0xffff0000, v193
	v_lshlrev_b32_e32 v58, 16, v193
	v_pk_fma_f32 v[50:51], v[30:31], v[62:63], v[50:51]
	v_pk_fma_f32 v[46:47], v[38:39], v[58:59], v[46:47]
	s_or_b64 exec, exec, s[26:27]
	v_cmp_lt_i32_e32 vcc, -1, v56
	s_and_saveexec_b64 s[26:27], vcc
	s_cbranch_execz .LBB0_2282
.LBB0_2290:
	v_and_b32_e32 v61, 0xffff0000, v194
	v_lshlrev_b32_e32 v60, 16, v194
	v_pk_fma_f32 v[52:53], v[32:33], v[60:61], v[52:53]
	v_and_b32_e32 v61, 0xffff0000, v195
	v_lshlrev_b32_e32 v60, 16, v195
	v_and_b32_e32 v57, 0xffff0000, v196
	v_lshlrev_b32_e32 v56, 16, v196
	v_pk_fma_f32 v[48:49], v[40:41], v[56:57], v[48:49]
	v_and_b32_e32 v57, 0xffff0000, v197
	v_lshlrev_b32_e32 v56, 16, v197
	v_pk_fma_f32 v[50:51], v[34:35], v[60:61], v[50:51]
	v_pk_fma_f32 v[46:47], v[42:43], v[56:57], v[46:47]
	s_branch .LBB0_2282
.LBB0_2291:
	s_waitcnt vmcnt(0)
	s_or_b64 exec, exec, s[16:17]
	s_waitcnt lgkmcnt(0)
	s_barrier
	s_and_saveexec_b64 s[70:71], s[10:11]
	s_cbranch_execz .LBB0_2258
	v_readlane_b32 s4, v242, 20
	v_readlane_b32 s5, v242, 21
	s_lshl_b64 s[4:5], s[4:5], 2
	s_add_u32 s20, s20, s4
	s_addc_u32 s21, s21, s5
	v_readlane_b32 s4, v242, 26
	v_readlane_b32 s5, v242, 27
	s_lshl_b64 s[4:5], s[4:5], 2
	s_add_u32 s4, s22, s4
	s_addc_u32 s5, s23, s5
	s_add_u32 s76, s90, 0x9800000
	s_addc_u32 s77, s91, 0
	s_lshl_b32 s22, s97, 2
	s_lshl_b64 s[16:17], s[18:19], 8
	s_or_b32 s16, s16, s22
	s_or_b64 s[16:17], s[16:17], s[48:49]
	s_lshl_b64 s[16:17], s[16:17], 14
	s_add_u32 s16, s90, s16
	v_or_b32_e32 v6, s96, v132
	s_addc_u32 s17, s91, s17
	v_mov_b32_e32 v83, v11
	v_lshlrev_b32_e32 v10, 2, v6
	v_lshl_add_u64 v[2:3], s[16:17], 0, v[82:83]
	s_mov_b64 s[16:17], 0x17100000
	v_lshl_add_u64 v[84:85], s[4:5], 0, v[10:11]
	s_mov_b64 s[4:5], 0x17104000
	v_lshl_add_u64 v[4:5], v[2:3], 0, s[16:17]
	v_mov_b32_e32 v75, v11
	v_mov_b32_e32 v77, v11
	v_mov_b32_e32 v79, v11
	v_mov_b32_e32 v81, v11
	v_lshl_add_u64 v[2:3], v[2:3], 0, s[4:5]
	s_lshl_b32 s4, s48, 2
	v_or_b32_e32 v8, 64, v6
	v_lshl_add_u64 v[86:87], v[4:5], 0, v[74:75]
	v_lshl_add_u64 v[88:89], v[4:5], 0, v[76:77]
	v_lshl_add_u64 v[90:91], v[4:5], 0, v[78:79]
	v_lshl_add_u64 v[92:93], v[4:5], 0, v[80:81]
	v_lshl_add_u64 v[94:95], v[2:3], 0, v[74:75]
	v_lshl_add_u64 v[96:97], v[2:3], 0, v[76:77]
	v_lshl_add_u64 v[98:99], v[2:3], 0, v[78:79]
	v_lshl_add_u64 v[100:101], v[2:3], 0, v[80:81]
	s_add_u32 s62, s20, s4
	v_or_b32_e32 v2, 16, v6
	v_or_b32_e32 v4, 32, v6
	s_waitcnt vmcnt(7)
	v_or_b32_e32 v12, 48, v6
	v_or_b32_e32 v14, 0x50, v6
	s_waitcnt vmcnt(6)
	v_or_b32_e32 v16, 0x60, v6
	v_or_b32_e32 v18, 0x70, v6
	s_addc_u32 s63, s21, 0
	s_mov_b64 s[40:41], 0
	s_lshl_b32 s48, s96, 1
	v_lshlrev_b32_e32 v10, 1, v6
	v_lshlrev_b32_e32 v102, 1, v2
	v_lshlrev_b32_e32 v104, 1, v4
	v_lshlrev_b32_e32 v106, 1, v12
	v_lshlrev_b32_e32 v108, 1, v8
	v_lshlrev_b32_e32 v110, 1, v14
	v_lshlrev_b32_e32 v112, 1, v16
	v_lshlrev_b32_e32 v114, 1, v18
	v_mov_b32_e32 v75, v67
	s_branch .LBB0_2295
